# v33 + FoX main loop: next step's barrier-independent LDS reads (bias rows, Q fragments) issued before the step barrier; only K-fragment reads stay behind it (loop-edge rotation, guide 7.11)
# speedup vs baseline: 1.0025x; 1.0012x over previous
.LBB0_335:
	v_add_f32_e32 v68, 0, v68
	v_add_f32_e32 v68, v69, v68
	v_add_f32_e32 v68, v70, v68
	v_add_f32_e32 v68, v71, v68
	v_add_f32_e32 v68, v72, v68
	v_add_f32_e32 v68, v73, v68
	v_add_f32_e32 v68, v74, v68
	v_add_f32_e32 v68, v75, v68
	v_add_f32_e32 v68, v76, v68
	v_add_f32_e32 v68, v77, v68
	v_add_f32_e32 v68, v78, v68
	v_add_f32_e32 v68, v79, v68
	v_add_f32_e32 v68, v80, v68
	v_add_f32_e32 v68, v81, v68
	v_add_f32_e32 v68, v82, v68
	v_add_f32_e32 v68, v83, v68
	v_add_f32_e32 v68, v84, v68
	v_add_f32_e32 v68, v85, v68
	v_add_f32_e32 v68, v86, v68
	v_add_f32_e32 v68, v87, v68
	v_add_f32_e32 v68, v88, v68
	v_add_f32_e32 v68, v89, v68
	v_add_f32_e32 v68, v90, v68
	v_add_f32_e32 v68, v91, v68
	v_add_f32_e32 v68, v92, v68
	v_add_f32_e32 v68, v93, v68
	v_add_f32_e32 v68, v94, v68
	v_add_f32_e32 v68, v95, v68
	v_add_f32_e32 v64, v64, v68
	v_add_f32_e32 v64, v65, v64
	v_add_f32_e32 v64, v66, v64
	v_add_f32_e32 v191, v67, v64
	s_and_b64 vcc, exec, s[48:49]
	s_waitcnt lgkmcnt(0)
	s_barrier
	s_cbranch_vccnz .LBB0_359
	s_add_i32 s62, s55, -3
	s_add_i32 s63, s16, 0
	s_and_b64 s[4:5], s[90:91], exec
	s_cselect_b32 s64, 0, 0x2080
	s_lshl_b32 s4, s17, 6
	s_sub_i32 s4, s56, s4
	s_add_i32 s16, s64, 0
	s_sub_i32 s90, s4, 64
	s_lshl_b32 s4, s56, 2
	s_lshl_b32 s5, s17, 8
	v_add_u32_e32 v64, s63, v143
	v_add3_u32 v65, s16, v146, v147
	v_add3_u32 v66, s63, v146, v147
	s_sub_i32 s4, s4, s5
	v_add_u32_e32 v192, s4, v184
	v_add_u32_e32 v193, v64, v141
	v_add_u32_e32 v194, v65, v148
	v_add_u32_e32 v195, v66, v148
	s_mov_b32 s99, 0
.LBB0_337:
	s_add_i32 s4, s90, 0x80
	s_ashr_i32 s5, s4, 31
	s_lshl_b64 s[4:5], s[4:5], 7
	v_lshl_add_u64 v[198:199], v[132:133], 0, s[4:5]
	global_load_dwordx4 v[100:103], v[198:199], off
	s_add_i32 s56, s57, 2
	s_cmp_lt_u32 s56, s55
	s_cselect_b64 s[4:5], -1, 0
	s_cmp_ge_u32 s56, s55
	s_cbranch_scc1 .LBB0_339
	s_add_i32 s48, s90, 64
	s_ashr_i32 s49, s48, 31
	s_lshl_b64 s[48:49], s[48:49], 7
	v_lshl_add_u64 v[198:199], v[130:131], 0, s[48:49]
	global_load_dwordx4 v[96:99], v[198:199], off
.LBB0_339:
	s_cmp_lg_u32 s99, 0
	s_cbranch_scc1 .Lfx_hoisted_8013
	ds_read_b128 v[92:95], v192 offset:352
	ds_read_b128 v[88:91], v192 offset:320
	ds_read_b128 v[80:83], v192 offset:256
	ds_read_b128 v[84:87], v192 offset:288
	ds_read_b128 v[202:205], v189 offset:60416
	ds_read_b128 v[64:67], v192 offset:384
	ds_read_b128 v[68:71], v192 offset:416
	ds_read_b128 v[72:75], v192 offset:448
	ds_read_b128 v[76:79], v192 offset:480
	ds_read_b128 v[210:213], v189 offset:61440
.Lfx_hoisted_8013:
	ds_read_b128 v[198:201], v193
	ds_read_b128 v[206:209], v193 offset:512
	s_waitcnt lgkmcnt(1)
	v_mfma_f32_32x32x16_bf16 v[80:95], v[198:201], v[202:205], v[80:95]
	ds_read_b128 v[198:201], v193 offset:2080
	v_max3_f32 v197, v48, s94, v49
	v_max3_f32 v197, v197, v50, v51
	s_waitcnt lgkmcnt(1)
	v_mfma_f32_32x32x16_bf16 v[64:79], v[206:209], v[202:205], v[64:79]
	ds_read_b128 v[202:205], v193 offset:2592
	ds_read_b128 v[206:209], v189 offset:62464
	v_max3_f32 v197, v197, v52, v53
	v_max3_f32 v197, v197, v54, v55
	s_waitcnt lgkmcnt(2)
	v_mfma_f32_32x32x16_bf16 v[80:95], v[198:201], v[210:213], v[80:95]
	ds_read_b128 v[198:201], v193 offset:4160
	v_max3_f32 v197, v197, v56, v57
	v_max3_f32 v197, v197, v58, v59
	s_waitcnt lgkmcnt(2)
	v_mfma_f32_32x32x16_bf16 v[64:79], v[202:205], v[210:213], v[64:79]
	ds_read_b128 v[202:205], v193 offset:4672
	ds_read_b128 v[210:213], v189 offset:63488
	v_max3_f32 v197, v197, v60, v61
	v_max3_f32 v197, v197, v62, v63
	s_waitcnt lgkmcnt(2)
	v_mfma_f32_32x32x16_bf16 v[80:95], v[198:201], v[206:209], v[80:95]
	ds_read_b128 v[198:201], v193 offset:6240
	v_max3_f32 v197, v197, v32, v33
	v_max3_f32 v197, v197, v34, v35
	s_waitcnt lgkmcnt(2)
	v_mfma_f32_32x32x16_bf16 v[64:79], v[202:205], v[206:209], v[64:79]
	ds_read_b128 v[202:205], v193 offset:6752
	v_max3_f32 v197, v197, v36, v37
	v_max3_f32 v197, v197, v38, v39
	s_waitcnt lgkmcnt(1)
	v_mfma_f32_32x32x16_bf16 v[80:95], v[198:201], v[210:213], v[80:95]
	v_max3_f32 v197, v197, v40, v41
	v_max3_f32 v197, v197, v42, v43
	s_waitcnt lgkmcnt(0)
	v_mfma_f32_32x32x16_bf16 v[64:79], v[202:205], v[210:213], v[64:79]
	v_max3_f32 v197, v197, v44, v45
	v_max3_f32 v197, v197, v46, v47
	v_mov_b32_e32 v198, v197
	v_mov_b32_e32 v199, v197
	s_nop 1
	v_permlane32_swap_b32_e32 v198, v199
	v_cndmask_b32_e64 v198, v198, v199, s[36:37]
	v_max_f32_e32 v198, v198, v198
	v_max_f32_e32 v197, v197, v198
	v_add_f32_e32 v198, 0x40c00000, v196
	v_cmp_gt_f32_e32 vcc, v197, v198
	s_nop 1
	v_cndmask_b32_e32 v236, v196, v197, vcc
	v_sub_f32_e32 v197, v196, v236
	v_exp_f32_e32 v197, v197
	v_cmp_neq_f32_e32 vcc, v236, v196
	s_cbranch_vccz .LBB0_343
	s_and_saveexec_b64 s[48:49], s[36:37]
	ds_write_b32 v176, v197 offset:58112
	s_or_b64 exec, exec, s[48:49]
	v_add_u32_e32 v196, s75, v108
	ds_read_b128 v[198:201], v196 offset:58208
	ds_read_b128 v[202:205], v196 offset:58176
	ds_read_b128 v[206:209], v196 offset:58144
	ds_read_b128 v[210:213], v196 offset:58112
	s_waitcnt lgkmcnt(3)
	v_pk_mul_f32 v[28:29], v[28:29], v[198:199]
	s_waitcnt lgkmcnt(2)
	v_pk_mul_f32 v[24:25], v[24:25], v[202:203]
	s_waitcnt lgkmcnt(1)
	v_pk_mul_f32 v[20:21], v[20:21], v[206:207]
	s_waitcnt lgkmcnt(0)
	v_pk_mul_f32 v[16:17], v[16:17], v[210:211]
	v_pk_mul_f32 v[12:13], v[12:13], v[198:199]
	v_pk_mul_f32 v[8:9], v[8:9], v[202:203]
	v_pk_mul_f32 v[4:5], v[4:5], v[206:207]
	v_pk_mul_f32 v[30:31], v[30:31], v[200:201]
	v_pk_mul_f32 v[26:27], v[26:27], v[204:205]
	v_pk_mul_f32 v[22:23], v[22:23], v[208:209]
	v_pk_mul_f32 v[18:19], v[18:19], v[212:213]
	v_pk_mul_f32 v[14:15], v[14:15], v[200:201]
	v_pk_mul_f32 v[10:11], v[10:11], v[204:205]
	v_pk_mul_f32 v[6:7], v[6:7], v[208:209]
	v_pk_mul_f32 v[2:3], v[2:3], v[212:213]
	v_pk_mul_f32 v[0:1], v[0:1], v[210:211]

.LBB0_345:
	s_and_b64 vcc, exec, s[48:49]
	ds_read_b128 v[60:63], v192 offset:96
	ds_read_b128 v[56:59], v192 offset:64
	ds_read_b128 v[48:51], v192
	ds_read_b128 v[52:55], v192 offset:32
	ds_read_b128 v[242:245], v189 offset:60416
	ds_read_b128 v[32:35], v192 offset:128
	ds_read_b128 v[36:39], v192 offset:160
	ds_read_b128 v[40:43], v192 offset:192
	ds_read_b128 v[44:47], v192 offset:224
	ds_read_b128 v[250:253], v189 offset:61440
	s_waitcnt lgkmcnt(10)
	s_barrier
	s_cbranch_vccnz .LBB0_347
	s_add_i32 s4, s90, 64
	s_ashr_i32 s5, s4, 31
	s_lshl_b64 s[4:5], s[4:5], 7
	v_lshl_add_u64 v[238:239], v[132:133], 0, s[4:5]
	global_load_dwordx4 v[100:103], v[238:239], off
.LBB0_347:
	s_cmp_lt_u32 s57, s62
	s_cselect_b64 s[4:5], -1, 0
	s_cmp_ge_u32 s57, s62
	s_cbranch_scc1 .LBB0_349
	s_ashr_i32 s91, s90, 31
	s_lshl_b64 vcc, s[90:91], 7
	v_lshl_add_u64 v[238:239], v[130:131], 0, vcc
	global_load_dwordx4 v[96:99], v[238:239], off
.LBB0_349:
	v_add_u32_e32 v196, s64, v144
	ds_read_b128 v[238:241], v196
	ds_read_b128 v[246:249], v196 offset:512
	s_waitcnt lgkmcnt(1)
	v_mfma_f32_32x32x16_bf16 v[48:63], v[238:241], v[242:245], v[48:63]
	ds_read_b128 v[238:241], v196 offset:2080
	v_max3_f32 v237, v80, s94, v81
	v_max3_f32 v237, v237, v82, v83
	v_add_f32_e32 v198, 0, v198
	v_add_f32_e32 v198, v199, v198
	v_add_f32_e32 v198, v200, v198
	v_add_f32_e32 v198, v201, v198
	v_add_f32_e32 v198, v202, v198
	s_waitcnt lgkmcnt(1)
	v_mfma_f32_32x32x16_bf16 v[32:47], v[246:249], v[242:245], v[32:47]
	ds_read_b128 v[242:245], v196 offset:2592
	ds_read_b128 v[246:249], v189 offset:62464
	v_max3_f32 v237, v237, v84, v85
	v_max3_f32 v237, v237, v86, v87
	v_add_f32_e32 v198, v203, v198
	v_add_f32_e32 v198, v204, v198
	v_add_f32_e32 v198, v205, v198
	v_add_f32_e32 v198, v206, v198
	v_add_f32_e32 v198, v207, v198
	s_waitcnt lgkmcnt(2)
	v_mfma_f32_32x32x16_bf16 v[48:63], v[238:241], v[250:253], v[48:63]
	ds_read_b128 v[238:241], v196 offset:4160
	v_max3_f32 v237, v237, v88, v89
	v_max3_f32 v237, v237, v90, v91
	v_add_f32_e32 v198, v208, v198
	v_add_f32_e32 v198, v209, v198
	v_add_f32_e32 v198, v210, v198
	v_add_f32_e32 v198, v211, v198
	v_add_f32_e32 v198, v212, v198
	s_waitcnt lgkmcnt(2)
	v_mfma_f32_32x32x16_bf16 v[32:47], v[242:245], v[250:253], v[32:47]
	ds_read_b128 v[242:245], v196 offset:4672
	ds_read_b128 v[250:253], v189 offset:63488
	v_max3_f32 v237, v237, v92, v93
	v_max3_f32 v237, v237, v94, v95
	v_add_f32_e32 v198, v213, v198
	v_add_f32_e32 v198, v214, v198
	v_add_f32_e32 v198, v215, v198
	v_add_f32_e32 v198, v216, v198
	v_add_f32_e32 v198, v217, v198
	s_waitcnt lgkmcnt(2)
	v_mfma_f32_32x32x16_bf16 v[48:63], v[238:241], v[246:249], v[48:63]
	ds_read_b128 v[238:241], v196 offset:6240
	v_max3_f32 v237, v237, v64, v65
	v_max3_f32 v237, v237, v66, v67
	v_add_f32_e32 v198, v218, v198
	v_add_f32_e32 v198, v219, v198
	v_add_f32_e32 v198, v220, v198
	v_add_f32_e32 v198, v221, v198
	v_add_f32_e32 v198, v222, v198
	s_waitcnt lgkmcnt(2)
	v_mfma_f32_32x32x16_bf16 v[32:47], v[242:245], v[246:249], v[32:47]
	ds_read_b128 v[242:245], v196 offset:6752
	v_max3_f32 v237, v237, v68, v69
	v_max3_f32 v237, v237, v70, v71
	v_add_f32_e32 v198, v223, v198
	v_add_f32_e32 v198, v224, v198
	v_add_f32_e32 v198, v225, v198
	v_add_f32_e32 v198, v226, v198
	v_add_f32_e32 v198, v227, v198
	s_waitcnt lgkmcnt(1)
	v_mfma_f32_32x32x16_bf16 v[48:63], v[238:241], v[250:253], v[48:63]
	v_max3_f32 v196, v237, v72, v73
	v_max3_f32 v196, v196, v74, v75
	v_add_f32_e32 v198, v228, v198
	v_add_f32_e32 v198, v229, v198
	v_fmac_f32_e32 v198, v191, v197
	s_waitcnt lgkmcnt(0)
	v_mfma_f32_32x32x16_bf16 v[32:47], v[242:245], v[250:253], v[32:47]
	v_max3_f32 v196, v196, v76, v77
	v_max3_f32 v196, v196, v78, v79
	v_mov_b32_e32 v237, v196
	v_mov_b32_e32 v238, v196
	s_nop 1
	v_permlane32_swap_b32_e32 v237, v238
	v_cndmask_b32_e64 v237, v237, v238, s[36:37]
	v_max_f32_e32 v237, v237, v237
	v_max_f32_e32 v196, v196, v237
	v_add_f32_e32 v237, 0x40c00000, v236
	v_cmp_gt_f32_e32 vcc, v196, v237
	s_nop 1
	v_cndmask_b32_e32 v196, v236, v196, vcc
	v_sub_f32_e32 v237, v236, v196
	v_exp_f32_e32 v237, v237
	v_cmp_neq_f32_e32 vcc, v196, v236
	s_cbranch_vccz .LBB0_353
	s_and_saveexec_b64 vcc, s[36:37]
	ds_write_b32 v176, v237 offset:58112
	s_or_b64 exec, exec, vcc
	v_add_u32_e32 v236, s75, v108
	ds_read_b128 v[238:241], v236 offset:58208
	ds_read_b128 v[242:245], v236 offset:58176
	ds_read_b128 v[246:249], v236 offset:58144
	ds_read_b128 v[250:253], v236 offset:58112
	s_waitcnt lgkmcnt(3)
	v_pk_mul_f32 v[12:13], v[12:13], v[238:239]
	s_waitcnt lgkmcnt(2)
	v_pk_mul_f32 v[8:9], v[8:9], v[242:243]
	s_waitcnt lgkmcnt(1)
	v_pk_mul_f32 v[4:5], v[4:5], v[246:247]
	v_pk_mul_f32 v[14:15], v[14:15], v[240:241]
	v_pk_mul_f32 v[10:11], v[10:11], v[244:245]
	v_pk_mul_f32 v[6:7], v[6:7], v[248:249]
	s_waitcnt lgkmcnt(0)
	v_pk_mul_f32 v[2:3], v[2:3], v[252:253]
	v_pk_mul_f32 v[0:1], v[0:1], v[250:251]
	v_pk_mul_f32 v[28:29], v[28:29], v[238:239]
	v_pk_mul_f32 v[24:25], v[24:25], v[242:243]
	v_pk_mul_f32 v[20:21], v[20:21], v[246:247]
	v_pk_mul_f32 v[30:31], v[30:31], v[240:241]
	v_pk_mul_f32 v[26:27], v[26:27], v[244:245]
	v_pk_mul_f32 v[22:23], v[22:23], v[248:249]
	v_pk_mul_f32 v[18:19], v[18:19], v[252:253]
	v_pk_mul_f32 v[16:17], v[16:17], v[250:251]

.LBB0_357:
	v_add_f32_e32 v80, 0, v80
	v_add_f32_e32 v80, v81, v80
	v_add_f32_e32 v80, v82, v80
	v_add_f32_e32 v80, v83, v80
	v_add_f32_e32 v80, v84, v80
	v_add_f32_e32 v80, v85, v80
	v_add_f32_e32 v80, v86, v80
	v_add_f32_e32 v80, v87, v80
	v_add_f32_e32 v80, v88, v80
	v_add_f32_e32 v80, v89, v80
	v_add_f32_e32 v80, v90, v80
	v_add_f32_e32 v80, v91, v80
	v_add_f32_e32 v80, v92, v80
	v_add_f32_e32 v80, v93, v80
	v_add_f32_e32 v80, v94, v80
	v_add_f32_e32 v80, v95, v80
	v_add_f32_e32 v64, v64, v80
	v_add_f32_e32 v64, v65, v64
	v_add_f32_e32 v64, v66, v64
	v_add_f32_e32 v64, v67, v64
	v_add_f32_e32 v64, v68, v64
	v_add_f32_e32 v64, v69, v64
	v_add_f32_e32 v64, v70, v64
	v_add_f32_e32 v64, v71, v64
	v_add_f32_e32 v64, v72, v64
	v_add_f32_e32 v64, v73, v64
	v_add_f32_e32 v64, v74, v64
	v_add_f32_e32 v64, v75, v64
	v_add_f32_e32 v64, v76, v64
	v_add_f32_e32 v64, v77, v64
	v_add_f32_e32 v64, v78, v64
	v_add_f32_e32 v191, v79, v64
	s_addk_i32 s90, 0xff80
	s_add_i32 s4, s56, 1
	v_fmac_f32_e32 v191, v198, v237
	s_cmp_lt_u32 s4, s55
	v_add_u32_e32 v192, 0xfffffe00, v192
	s_cbranch_scc0 .Lfx_exit
	ds_read_b128 v[92:95], v192 offset:352
	ds_read_b128 v[88:91], v192 offset:320
	ds_read_b128 v[80:83], v192 offset:256
	ds_read_b128 v[84:87], v192 offset:288
	ds_read_b128 v[202:205], v189 offset:60416
	ds_read_b128 v[64:67], v192 offset:384
	ds_read_b128 v[68:71], v192 offset:416
	ds_read_b128 v[72:75], v192 offset:448
	ds_read_b128 v[76:79], v192 offset:480
	ds_read_b128 v[210:213], v189 offset:61440
	s_mov_b32 s99, 1
	s_waitcnt lgkmcnt(10)
	s_barrier
	s_mov_b32 s57, s56
	s_branch .LBB0_337
.Lfx_exit:
	s_waitcnt lgkmcnt(0)
	s_barrier
	s_branch .LBB0_360
.LBB0_359:
	s_mov_b32 s56, s57
